# merge GEMM epilogue: 5 of the 8 g_c gate quads kept from the second mid rescale (same tile) in phase-free registers, their loads and the vmcnt(0) behind the next unit's staging DMAs dropped; 3 remaini
# speedup vs baseline: 1.0012x; 1.0012x over previous
.LBB0_3766:
	s_cmpk_eq_i32 s20, 0x1000
	s_cselect_b32 s22, 0, 16
	s_add_i32 s22, s53, s22
	v_mov_b32_e32 v2, v183
	v_mov_b32_e32 v4, v182
	s_ashr_i32 s23, s22, 31
	s_lshl_b64 s[22:23], s[22:23], 16
	v_lshl_add_u32 v2, v2, 4, v4
	s_add_u32 s24, s36, s22
	v_add_u32_e32 v4, s39, v2
	s_addc_u32 s25, s37, s23
	s_add_u32 s22, s24, 0x100000
	v_ashrrev_i32_e32 v5, 31, v4
	s_addc_u32 s23, s25, 0
	v_lshlrev_b64 v[134:135], 4, v[4:5]
	v_lshl_add_u64 v[136:137], s[24:25], 0, v[134:135]
	v_lshl_add_u64 v[134:135], s[22:23], 0, v[134:135]
	global_load_dwordx4 v[158:161], v[136:137], off nt
	global_load_dwordx4 v[162:165], v[134:135], off nt
	v_add_u32_e32 v4, 0x200, v4
	v_ashrrev_i32_e32 v5, 31, v4
	v_lshlrev_b64 v[4:5], 4, v[4:5]
	v_lshl_add_u64 v[134:135], s[24:25], 0, v[4:5]
	v_lshl_add_u64 v[4:5], s[22:23], 0, v[4:5]
	global_load_dwordx4 v[150:153], v[134:135], off nt
	global_load_dwordx4 v[154:157], v[4:5], off nt
	v_add_u32_e32 v4, s40, v2
	v_ashrrev_i32_e32 v5, 31, v4
	v_lshlrev_b64 v[4:5], 4, v[4:5]
	v_lshl_add_u64 v[134:135], s[24:25], 0, v[4:5]
	v_lshl_add_u64 v[4:5], s[22:23], 0, v[4:5]
	global_load_dwordx4 v[142:145], v[134:135], off nt
	global_load_dwordx4 v[146:149], v[4:5], off nt
	v_add_u32_e32 v4, s42, v2
	v_ashrrev_i32_e32 v5, 31, v4
	v_lshlrev_b64 v[4:5], 4, v[4:5]
	v_lshl_add_u64 v[134:135], s[24:25], 0, v[4:5]
	v_lshl_add_u64 v[4:5], s[22:23], 0, v[4:5]
	global_load_dwordx4 v[134:137], v[134:135], off nt
	s_andn2_b64 vcc, exec, s[8:9]
	global_load_dwordx4 v[138:141], v[4:5], off nt
	s_waitcnt vmcnt(4)
	v_mov_b32_e32 v240, v162
	v_mov_b32_e32 v241, v163
	v_mov_b32_e32 v242, v164
	v_mov_b32_e32 v243, v165
	v_mov_b32_e32 v244, v154
	v_mov_b32_e32 v245, v155
	v_mov_b32_e32 v246, v156
	v_mov_b32_e32 v247, v157
	v_cvt_f32_ubyte1_e32 v191, v158
	v_cvt_f32_ubyte0_e32 v4, v162
	v_cvt_f32_ubyte1_e32 v5, v162
	v_rcp_iflag_f32_e32 v4, v4
	v_rcp_iflag_f32_e32 v5, v5
	v_cvt_f32_ubyte0_e32 v190, v158
	v_cvt_f32_ubyte2_e32 v186, v162
	v_cvt_f32_ubyte3_e32 v162, v162
	v_pk_mul_f32 v[4:5], v[4:5], v[190:191]
	v_rcp_iflag_f32_e32 v186, v186
	v_rcp_iflag_f32_e32 v187, v162
	v_pk_mul_f32 v[130:131], v[130:131], v[4:5]
	v_cvt_f32_ubyte0_e32 v4, v163
	v_cvt_f32_ubyte1_e32 v5, v163
	v_rcp_iflag_f32_e32 v4, v4
	v_rcp_iflag_f32_e32 v5, v5
	v_cvt_f32_ubyte3_e32 v189, v158
	v_cvt_f32_ubyte2_e32 v188, v158
	v_cvt_f32_ubyte2_e32 v158, v163
	v_pk_mul_f32 v[186:187], v[186:187], v[188:189]
	v_rcp_iflag_f32_e32 v162, v158
	v_cvt_f32_ubyte3_e32 v158, v163
	v_cvt_f32_ubyte1_e32 v189, v159
	v_cvt_f32_ubyte0_e32 v188, v159
	v_rcp_iflag_f32_e32 v163, v158
	v_pk_mul_f32 v[4:5], v[4:5], v[188:189]
	v_pk_mul_f32 v[132:133], v[132:133], v[186:187]
	v_pk_mul_f32 v[126:127], v[126:127], v[4:5]
	v_cvt_f32_ubyte0_e32 v4, v164
	v_cvt_f32_ubyte1_e32 v5, v164
	v_rcp_iflag_f32_e32 v4, v4
	v_rcp_iflag_f32_e32 v5, v5
	v_cvt_f32_ubyte3_e32 v187, v159
	v_cvt_f32_ubyte2_e32 v186, v159
	v_pk_mul_f32 v[158:159], v[162:163], v[186:187]
	v_cvt_f32_ubyte1_e32 v187, v160
	v_pk_mul_f32 v[128:129], v[128:129], v[158:159]
	v_cvt_f32_ubyte2_e32 v158, v164
	v_cvt_f32_ubyte3_e32 v159, v164
	v_cvt_f32_ubyte0_e32 v186, v160
	v_rcp_iflag_f32_e32 v158, v158
	v_rcp_iflag_f32_e32 v159, v159
	v_pk_mul_f32 v[4:5], v[4:5], v[186:187]
	v_cvt_f32_ubyte3_e32 v163, v160
	v_pk_mul_f32 v[122:123], v[122:123], v[4:5]
	v_cvt_f32_ubyte0_e32 v4, v165
	v_cvt_f32_ubyte1_e32 v5, v165
	v_rcp_iflag_f32_e32 v4, v4
	v_rcp_iflag_f32_e32 v5, v5
	v_cvt_f32_ubyte2_e32 v162, v160
	v_pk_mul_f32 v[158:159], v[158:159], v[162:163]
	v_cvt_f32_ubyte0_e32 v164, v161
	v_pk_mul_f32 v[124:125], v[124:125], v[158:159]
	v_cvt_f32_ubyte2_e32 v158, v165
	v_cvt_f32_ubyte3_e32 v159, v165
	v_cvt_f32_ubyte1_e32 v165, v161
	v_pk_mul_f32 v[4:5], v[4:5], v[164:165]
	v_rcp_iflag_f32_e32 v158, v158
	v_rcp_iflag_f32_e32 v159, v159
	v_pk_mul_f32 v[118:119], v[118:119], v[4:5]
	v_cvt_f32_ubyte0_e32 v4, v154
	v_cvt_f32_ubyte1_e32 v5, v154
	v_rcp_iflag_f32_e32 v4, v4
	v_rcp_iflag_f32_e32 v5, v5
	v_cvt_f32_ubyte3_e32 v163, v161
	v_cvt_f32_ubyte2_e32 v162, v161
	v_pk_mul_f32 v[158:159], v[158:159], v[162:163]
	v_cvt_f32_ubyte1_e32 v163, v150
	v_cvt_f32_ubyte0_e32 v162, v150
	v_pk_mul_f32 v[120:121], v[120:121], v[158:159]
	v_cvt_f32_ubyte2_e32 v158, v154
	v_cvt_f32_ubyte3_e32 v154, v154
	v_pk_mul_f32 v[4:5], v[4:5], v[162:163]
	v_rcp_iflag_f32_e32 v158, v158
	v_rcp_iflag_f32_e32 v159, v154
	v_pk_mul_f32 v[114:115], v[114:115], v[4:5]
	v_cvt_f32_ubyte0_e32 v4, v155
	v_cvt_f32_ubyte1_e32 v5, v155
	v_rcp_iflag_f32_e32 v4, v4
	v_rcp_iflag_f32_e32 v5, v5
	v_cvt_f32_ubyte3_e32 v161, v150
	v_cvt_f32_ubyte2_e32 v160, v150
	v_cvt_f32_ubyte2_e32 v150, v155
	v_rcp_iflag_f32_e32 v154, v150
	v_cvt_f32_ubyte3_e32 v150, v155
	v_pk_mul_f32 v[158:159], v[158:159], v[160:161]
	v_rcp_iflag_f32_e32 v155, v150
	v_cvt_f32_ubyte1_e32 v161, v151
	v_cvt_f32_ubyte0_e32 v160, v151
	v_pk_mul_f32 v[4:5], v[4:5], v[160:161]
	v_pk_mul_f32 v[116:117], v[116:117], v[158:159]
	v_pk_mul_f32 v[110:111], v[110:111], v[4:5]
	v_cvt_f32_ubyte0_e32 v4, v156
	v_cvt_f32_ubyte1_e32 v5, v156
	v_cvt_f32_ubyte3_e32 v159, v151
	v_cvt_f32_ubyte2_e32 v158, v151
	v_rcp_iflag_f32_e32 v4, v4
	v_rcp_iflag_f32_e32 v5, v5
	v_pk_mul_f32 v[150:151], v[154:155], v[158:159]
	v_cvt_f32_ubyte1_e32 v159, v152
	v_pk_mul_f32 v[112:113], v[112:113], v[150:151]
	v_cvt_f32_ubyte2_e32 v150, v156
	v_cvt_f32_ubyte3_e32 v151, v156
	v_rcp_iflag_f32_e32 v150, v150
	v_rcp_iflag_f32_e32 v151, v151
	v_cvt_f32_ubyte0_e32 v158, v152
	v_pk_mul_f32 v[4:5], v[4:5], v[158:159]
	v_cvt_f32_ubyte3_e32 v155, v152
	v_pk_mul_f32 v[106:107], v[106:107], v[4:5]
	v_cvt_f32_ubyte0_e32 v4, v157
	v_cvt_f32_ubyte1_e32 v5, v157
	v_cvt_f32_ubyte2_e32 v154, v152
	v_rcp_iflag_f32_e32 v4, v4
	v_rcp_iflag_f32_e32 v5, v5
	v_pk_mul_f32 v[150:151], v[150:151], v[154:155]
	v_cvt_f32_ubyte0_e32 v156, v153
	v_pk_mul_f32 v[108:109], v[108:109], v[150:151]
	v_cvt_f32_ubyte2_e32 v150, v157
	v_cvt_f32_ubyte3_e32 v151, v157
	v_rcp_iflag_f32_e32 v150, v150
	v_rcp_iflag_f32_e32 v151, v151
	v_cvt_f32_ubyte1_e32 v157, v153
	v_pk_mul_f32 v[4:5], v[4:5], v[156:157]
	v_cvt_f32_ubyte3_e32 v155, v153
	v_pk_mul_f32 v[102:103], v[102:103], v[4:5]
	v_add_u32_e32 v4, s43, v2
	v_cvt_f32_ubyte2_e32 v154, v153
	v_ashrrev_i32_e32 v5, 31, v4
	v_pk_mul_f32 v[150:151], v[150:151], v[154:155]
	v_lshlrev_b64 v[4:5], 4, v[4:5]
	v_pk_mul_f32 v[104:105], v[104:105], v[150:151]
	v_lshl_add_u64 v[150:151], s[24:25], 0, v[4:5]
	v_lshl_add_u64 v[4:5], s[22:23], 0, v[4:5]
	global_load_dwordx4 v[158:161], v[150:151], off nt
	global_load_dwordx4 v[162:165], v[4:5], off nt
	v_add_u32_e32 v4, s44, v2
	v_ashrrev_i32_e32 v5, 31, v4
	v_lshlrev_b64 v[4:5], 4, v[4:5]
	v_lshl_add_u64 v[150:151], s[24:25], 0, v[4:5]
	v_lshl_add_u64 v[4:5], s[22:23], 0, v[4:5]
	global_load_dwordx4 v[150:153], v[150:151], off nt
	s_waitcnt vmcnt(3)
	v_mov_b32_e32 v248, v146
	v_mov_b32_e32 v249, v147
	v_mov_b32_e32 v250, v148
	v_mov_b32_e32 v251, v149
	v_mov_b32_e32 v218, v138
	v_mov_b32_e32 v219, v139
	v_mov_b32_e32 v220, v140
	v_mov_b32_e32 v221, v141
	v_cvt_f32_ubyte1_e32 v191, v142
	global_load_dwordx4 v[154:157], v[4:5], off nt
	v_cvt_f32_ubyte0_e32 v4, v146
	v_cvt_f32_ubyte1_e32 v5, v146
	v_rcp_iflag_f32_e32 v4, v4
	v_rcp_iflag_f32_e32 v5, v5
	v_cvt_f32_ubyte0_e32 v190, v142
	v_cvt_f32_ubyte2_e32 v186, v146
	v_cvt_f32_ubyte3_e32 v146, v146
	v_pk_mul_f32 v[4:5], v[4:5], v[190:191]
	v_rcp_iflag_f32_e32 v186, v186
	v_rcp_iflag_f32_e32 v187, v146
	v_pk_mul_f32 v[98:99], v[98:99], v[4:5]
	v_cvt_f32_ubyte0_e32 v4, v147
	v_cvt_f32_ubyte1_e32 v5, v147
	v_rcp_iflag_f32_e32 v4, v4
	v_rcp_iflag_f32_e32 v5, v5
	v_cvt_f32_ubyte3_e32 v189, v142
	v_cvt_f32_ubyte2_e32 v188, v142
	v_cvt_f32_ubyte2_e32 v142, v147
	v_pk_mul_f32 v[186:187], v[186:187], v[188:189]
	v_rcp_iflag_f32_e32 v146, v142
	v_cvt_f32_ubyte3_e32 v142, v147
	v_cvt_f32_ubyte1_e32 v189, v143
	v_cvt_f32_ubyte0_e32 v188, v143
	v_rcp_iflag_f32_e32 v147, v142
	v_pk_mul_f32 v[4:5], v[4:5], v[188:189]
	v_pk_mul_f32 v[100:101], v[100:101], v[186:187]
	v_pk_mul_f32 v[94:95], v[94:95], v[4:5]
	v_cvt_f32_ubyte0_e32 v4, v148
	v_cvt_f32_ubyte1_e32 v5, v148
	v_rcp_iflag_f32_e32 v4, v4
	v_rcp_iflag_f32_e32 v5, v5
	v_cvt_f32_ubyte3_e32 v187, v143
	v_cvt_f32_ubyte2_e32 v186, v143
	v_pk_mul_f32 v[142:143], v[146:147], v[186:187]
	v_cvt_f32_ubyte1_e32 v187, v144
	v_pk_mul_f32 v[96:97], v[96:97], v[142:143]
	v_cvt_f32_ubyte2_e32 v142, v148
	v_cvt_f32_ubyte3_e32 v143, v148
	v_cvt_f32_ubyte0_e32 v186, v144
	v_rcp_iflag_f32_e32 v142, v142
	v_rcp_iflag_f32_e32 v143, v143
	v_pk_mul_f32 v[4:5], v[4:5], v[186:187]
	v_cvt_f32_ubyte3_e32 v147, v144
	v_pk_mul_f32 v[90:91], v[90:91], v[4:5]
	v_cvt_f32_ubyte0_e32 v4, v149
	v_cvt_f32_ubyte1_e32 v5, v149
	v_rcp_iflag_f32_e32 v4, v4
	v_rcp_iflag_f32_e32 v5, v5
	v_cvt_f32_ubyte2_e32 v146, v144
	v_pk_mul_f32 v[142:143], v[142:143], v[146:147]
	v_cvt_f32_ubyte0_e32 v148, v145
	v_pk_mul_f32 v[92:93], v[92:93], v[142:143]
	v_cvt_f32_ubyte2_e32 v142, v149
	v_cvt_f32_ubyte3_e32 v143, v149
	v_cvt_f32_ubyte1_e32 v149, v145
	v_pk_mul_f32 v[4:5], v[4:5], v[148:149]
	v_rcp_iflag_f32_e32 v142, v142
	v_rcp_iflag_f32_e32 v143, v143
	v_pk_mul_f32 v[86:87], v[86:87], v[4:5]
	v_cvt_f32_ubyte0_e32 v4, v138
	v_cvt_f32_ubyte1_e32 v5, v138
	v_rcp_iflag_f32_e32 v4, v4
	v_rcp_iflag_f32_e32 v5, v5
	v_cvt_f32_ubyte3_e32 v147, v145
	v_cvt_f32_ubyte2_e32 v146, v145
	v_pk_mul_f32 v[142:143], v[142:143], v[146:147]
	v_cvt_f32_ubyte1_e32 v147, v134
	v_cvt_f32_ubyte0_e32 v146, v134
	v_pk_mul_f32 v[88:89], v[88:89], v[142:143]
	v_cvt_f32_ubyte2_e32 v142, v138
	v_cvt_f32_ubyte3_e32 v138, v138
	v_pk_mul_f32 v[4:5], v[4:5], v[146:147]
	v_rcp_iflag_f32_e32 v142, v142
	v_rcp_iflag_f32_e32 v143, v138
	v_pk_mul_f32 v[82:83], v[82:83], v[4:5]
	v_cvt_f32_ubyte0_e32 v4, v139
	v_cvt_f32_ubyte1_e32 v5, v139
	v_rcp_iflag_f32_e32 v4, v4
	v_rcp_iflag_f32_e32 v5, v5
	v_cvt_f32_ubyte3_e32 v145, v134
	v_cvt_f32_ubyte2_e32 v144, v134
	v_cvt_f32_ubyte2_e32 v134, v139
	v_rcp_iflag_f32_e32 v138, v134
	v_cvt_f32_ubyte3_e32 v134, v139
	v_pk_mul_f32 v[142:143], v[142:143], v[144:145]
	v_rcp_iflag_f32_e32 v139, v134
	v_cvt_f32_ubyte1_e32 v145, v135
	v_cvt_f32_ubyte0_e32 v144, v135
	v_pk_mul_f32 v[4:5], v[4:5], v[144:145]
	v_pk_mul_f32 v[84:85], v[84:85], v[142:143]
	v_pk_mul_f32 v[78:79], v[78:79], v[4:5]
	v_cvt_f32_ubyte0_e32 v4, v140
	v_cvt_f32_ubyte1_e32 v5, v140
	v_cvt_f32_ubyte3_e32 v143, v135
	v_cvt_f32_ubyte2_e32 v142, v135
	v_rcp_iflag_f32_e32 v4, v4
	v_rcp_iflag_f32_e32 v5, v5
	v_pk_mul_f32 v[134:135], v[138:139], v[142:143]
	v_cvt_f32_ubyte1_e32 v143, v136
	v_pk_mul_f32 v[80:81], v[80:81], v[134:135]
	v_cvt_f32_ubyte2_e32 v134, v140
	v_cvt_f32_ubyte3_e32 v135, v140
	v_rcp_iflag_f32_e32 v134, v134
	v_rcp_iflag_f32_e32 v135, v135
	v_cvt_f32_ubyte0_e32 v142, v136
	v_pk_mul_f32 v[4:5], v[4:5], v[142:143]
	v_cvt_f32_ubyte3_e32 v139, v136
	v_pk_mul_f32 v[74:75], v[74:75], v[4:5]
	v_cvt_f32_ubyte0_e32 v4, v141
	v_cvt_f32_ubyte1_e32 v5, v141
	v_cvt_f32_ubyte2_e32 v138, v136
	v_rcp_iflag_f32_e32 v4, v4
	v_rcp_iflag_f32_e32 v5, v5
	v_pk_mul_f32 v[134:135], v[134:135], v[138:139]
	v_cvt_f32_ubyte0_e32 v140, v137
	v_pk_mul_f32 v[76:77], v[76:77], v[134:135]
	v_cvt_f32_ubyte2_e32 v134, v141
	v_cvt_f32_ubyte3_e32 v135, v141
	v_rcp_iflag_f32_e32 v134, v134
	v_rcp_iflag_f32_e32 v135, v135
	v_cvt_f32_ubyte1_e32 v141, v137
	v_pk_mul_f32 v[4:5], v[4:5], v[140:141]
	v_cvt_f32_ubyte3_e32 v139, v137
	v_pk_mul_f32 v[70:71], v[70:71], v[4:5]
	v_add_u32_e32 v4, s45, v2
	v_cvt_f32_ubyte2_e32 v138, v137
	v_ashrrev_i32_e32 v5, 31, v4
	v_pk_mul_f32 v[134:135], v[134:135], v[138:139]
	v_lshlrev_b64 v[4:5], 4, v[4:5]
	v_pk_mul_f32 v[72:73], v[72:73], v[134:135]
	v_lshl_add_u64 v[134:135], s[24:25], 0, v[4:5]
	v_lshl_add_u64 v[4:5], s[22:23], 0, v[4:5]
	global_load_dwordx4 v[142:145], v[134:135], off nt
	global_load_dwordx4 v[146:149], v[4:5], off nt
	v_add_u32_e32 v4, s46, v2
	v_ashrrev_i32_e32 v5, 31, v4
	v_lshlrev_b64 v[4:5], 4, v[4:5]
	v_lshl_add_u64 v[134:135], s[24:25], 0, v[4:5]
	v_lshl_add_u64 v[4:5], s[22:23], 0, v[4:5]
	global_load_dwordx4 v[134:137], v[134:135], off nt
	s_waitcnt vmcnt(3)
	v_mov_b32_e32 v222, v162
	v_mov_b32_e32 v223, v163
	v_mov_b32_e32 v224, v164
	v_mov_b32_e32 v225, v165
	v_cvt_f32_ubyte0_e32 v2, v162
	global_load_dwordx4 v[138:141], v[4:5], off nt
	v_rcp_iflag_f32_e32 v4, v2
	v_cvt_f32_ubyte1_e32 v2, v162
	v_rcp_iflag_f32_e32 v5, v2
	v_cvt_f32_ubyte2_e32 v2, v162
	v_rcp_iflag_f32_e32 v186, v2
	v_cvt_f32_ubyte3_e32 v2, v162
	v_cvt_f32_ubyte1_e32 v191, v158
	v_cvt_f32_ubyte0_e32 v190, v158
	v_rcp_iflag_f32_e32 v187, v2
	v_pk_mul_f32 v[4:5], v[4:5], v[190:191]
	v_cvt_f32_ubyte0_e32 v2, v163
	v_pk_mul_f32 v[66:67], v[66:67], v[4:5]
	v_rcp_iflag_f32_e32 v4, v2
	v_cvt_f32_ubyte1_e32 v2, v163
	v_rcp_iflag_f32_e32 v5, v2
	v_cvt_f32_ubyte3_e32 v189, v158
	v_cvt_f32_ubyte2_e32 v188, v158
	v_cvt_f32_ubyte2_e32 v2, v163
	v_pk_mul_f32 v[186:187], v[186:187], v[188:189]
	v_rcp_iflag_f32_e32 v162, v2
	v_cvt_f32_ubyte3_e32 v2, v163
	v_cvt_f32_ubyte1_e32 v189, v159
	v_cvt_f32_ubyte0_e32 v188, v159
	v_rcp_iflag_f32_e32 v163, v2
	v_pk_mul_f32 v[4:5], v[4:5], v[188:189]
	v_cvt_f32_ubyte0_e32 v2, v164
	v_pk_mul_f32 v[62:63], v[62:63], v[4:5]
	v_rcp_iflag_f32_e32 v4, v2
	v_cvt_f32_ubyte1_e32 v2, v164
	v_rcp_iflag_f32_e32 v5, v2
	v_pk_mul_f32 v[68:69], v[68:69], v[186:187]
	v_cvt_f32_ubyte3_e32 v187, v159
	v_cvt_f32_ubyte2_e32 v186, v159
	v_pk_mul_f32 v[158:159], v[162:163], v[186:187]
	v_cvt_f32_ubyte2_e32 v2, v164
	v_pk_mul_f32 v[64:65], v[64:65], v[158:159]
	v_rcp_iflag_f32_e32 v158, v2
	v_cvt_f32_ubyte3_e32 v2, v164
	v_cvt_f32_ubyte1_e32 v187, v160
	v_cvt_f32_ubyte0_e32 v186, v160
	v_rcp_iflag_f32_e32 v159, v2
	v_pk_mul_f32 v[4:5], v[4:5], v[186:187]
	v_cvt_f32_ubyte0_e32 v2, v165
	v_pk_mul_f32 v[58:59], v[58:59], v[4:5]
	v_rcp_iflag_f32_e32 v4, v2
	v_cvt_f32_ubyte1_e32 v2, v165
	v_rcp_iflag_f32_e32 v5, v2
	v_cvt_f32_ubyte3_e32 v163, v160
	v_cvt_f32_ubyte2_e32 v162, v160
	v_pk_mul_f32 v[158:159], v[158:159], v[162:163]
	v_cvt_f32_ubyte2_e32 v2, v165
	v_pk_mul_f32 v[60:61], v[60:61], v[158:159]
	v_rcp_iflag_f32_e32 v158, v2
	v_cvt_f32_ubyte3_e32 v2, v165
	v_cvt_f32_ubyte1_e32 v165, v161
	v_cvt_f32_ubyte0_e32 v164, v161
	v_rcp_iflag_f32_e32 v159, v2
	v_pk_mul_f32 v[4:5], v[4:5], v[164:165]
	v_cvt_f32_ubyte0_e32 v2, v154
	v_pk_mul_f32 v[54:55], v[54:55], v[4:5]
	v_rcp_iflag_f32_e32 v4, v2
	v_cvt_f32_ubyte1_e32 v2, v154
	v_rcp_iflag_f32_e32 v5, v2
	v_cvt_f32_ubyte3_e32 v163, v161
	v_cvt_f32_ubyte2_e32 v162, v161
	v_pk_mul_f32 v[158:159], v[158:159], v[162:163]
	v_cvt_f32_ubyte2_e32 v2, v154
	v_pk_mul_f32 v[56:57], v[56:57], v[158:159]
	v_rcp_iflag_f32_e32 v158, v2
	v_cvt_f32_ubyte3_e32 v2, v154
	v_cvt_f32_ubyte1_e32 v163, v150
	v_cvt_f32_ubyte0_e32 v162, v150
	v_rcp_iflag_f32_e32 v159, v2
	v_pk_mul_f32 v[4:5], v[4:5], v[162:163]
	v_cvt_f32_ubyte0_e32 v2, v155
	v_pk_mul_f32 v[50:51], v[50:51], v[4:5]
	v_rcp_iflag_f32_e32 v4, v2
	v_cvt_f32_ubyte1_e32 v2, v155
	v_rcp_iflag_f32_e32 v5, v2
	v_cvt_f32_ubyte3_e32 v161, v150
	v_cvt_f32_ubyte2_e32 v160, v150
	v_cvt_f32_ubyte2_e32 v2, v155
	v_pk_mul_f32 v[158:159], v[158:159], v[160:161]
	v_rcp_iflag_f32_e32 v154, v2
	v_cvt_f32_ubyte3_e32 v2, v155
	v_cvt_f32_ubyte1_e32 v161, v151
	v_cvt_f32_ubyte0_e32 v160, v151
	v_rcp_iflag_f32_e32 v155, v2
	v_pk_mul_f32 v[4:5], v[4:5], v[160:161]
	v_cvt_f32_ubyte0_e32 v2, v156
	v_pk_mul_f32 v[46:47], v[46:47], v[4:5]
	v_rcp_iflag_f32_e32 v4, v2
	v_cvt_f32_ubyte1_e32 v2, v156
	v_rcp_iflag_f32_e32 v5, v2
	v_pk_mul_f32 v[52:53], v[52:53], v[158:159]
	v_cvt_f32_ubyte3_e32 v159, v151
	v_cvt_f32_ubyte2_e32 v158, v151
	v_pk_mul_f32 v[150:151], v[154:155], v[158:159]
	v_cvt_f32_ubyte2_e32 v2, v156
	v_pk_mul_f32 v[48:49], v[48:49], v[150:151]
	v_rcp_iflag_f32_e32 v150, v2
	v_cvt_f32_ubyte3_e32 v2, v156
	v_cvt_f32_ubyte1_e32 v159, v152
	v_cvt_f32_ubyte0_e32 v158, v152
	v_rcp_iflag_f32_e32 v151, v2
	v_pk_mul_f32 v[4:5], v[4:5], v[158:159]
	v_cvt_f32_ubyte0_e32 v2, v157
	v_pk_mul_f32 v[42:43], v[42:43], v[4:5]
	v_rcp_iflag_f32_e32 v4, v2
	v_cvt_f32_ubyte1_e32 v2, v157
	v_rcp_iflag_f32_e32 v5, v2
	v_cvt_f32_ubyte3_e32 v155, v152
	v_cvt_f32_ubyte2_e32 v154, v152
	v_pk_mul_f32 v[150:151], v[150:151], v[154:155]
	v_cvt_f32_ubyte2_e32 v2, v157
	v_pk_mul_f32 v[44:45], v[44:45], v[150:151]
	v_rcp_iflag_f32_e32 v150, v2
	v_cvt_f32_ubyte3_e32 v2, v157
	v_cvt_f32_ubyte1_e32 v157, v153
	v_cvt_f32_ubyte0_e32 v156, v153
	v_rcp_iflag_f32_e32 v151, v2
	v_pk_mul_f32 v[4:5], v[4:5], v[156:157]
	s_waitcnt vmcnt(1)
	v_cvt_f32_ubyte0_e32 v2, v146
	v_pk_mul_f32 v[38:39], v[38:39], v[4:5]
	v_rcp_iflag_f32_e32 v4, v2
	v_cvt_f32_ubyte1_e32 v2, v146
	v_rcp_iflag_f32_e32 v5, v2
	v_cvt_f32_ubyte3_e32 v155, v153
	v_cvt_f32_ubyte2_e32 v154, v153
	v_pk_mul_f32 v[150:151], v[150:151], v[154:155]
	v_cvt_f32_ubyte2_e32 v2, v146
	v_pk_mul_f32 v[40:41], v[40:41], v[150:151]
	v_rcp_iflag_f32_e32 v150, v2
	v_cvt_f32_ubyte3_e32 v2, v146
	v_cvt_f32_ubyte1_e32 v155, v142
	v_cvt_f32_ubyte0_e32 v154, v142
	v_rcp_iflag_f32_e32 v151, v2
	v_pk_mul_f32 v[4:5], v[4:5], v[154:155]
	v_cvt_f32_ubyte0_e32 v2, v147
	v_pk_mul_f32 v[34:35], v[34:35], v[4:5]
	v_rcp_iflag_f32_e32 v4, v2
	v_cvt_f32_ubyte1_e32 v2, v147
	v_rcp_iflag_f32_e32 v5, v2
	v_cvt_f32_ubyte3_e32 v153, v142
	v_cvt_f32_ubyte2_e32 v152, v142
	v_cvt_f32_ubyte2_e32 v2, v147
	v_pk_mul_f32 v[150:151], v[150:151], v[152:153]
	v_rcp_iflag_f32_e32 v146, v2
	v_cvt_f32_ubyte3_e32 v2, v147
	v_cvt_f32_ubyte1_e32 v153, v143
	v_cvt_f32_ubyte0_e32 v152, v143
	v_rcp_iflag_f32_e32 v147, v2
	v_pk_mul_f32 v[4:5], v[4:5], v[152:153]
	v_cvt_f32_ubyte0_e32 v2, v148
	v_pk_mul_f32 v[30:31], v[30:31], v[4:5]
	v_rcp_iflag_f32_e32 v4, v2
	v_cvt_f32_ubyte1_e32 v2, v148
	v_rcp_iflag_f32_e32 v5, v2
	v_pk_mul_f32 v[36:37], v[36:37], v[150:151]
	v_cvt_f32_ubyte3_e32 v151, v143
	v_cvt_f32_ubyte2_e32 v150, v143
	v_pk_mul_f32 v[142:143], v[146:147], v[150:151]
	v_cvt_f32_ubyte2_e32 v2, v148
	v_pk_mul_f32 v[32:33], v[32:33], v[142:143]
	v_rcp_iflag_f32_e32 v142, v2
	v_cvt_f32_ubyte3_e32 v2, v148
	v_cvt_f32_ubyte1_e32 v151, v144
	v_cvt_f32_ubyte0_e32 v150, v144
	v_rcp_iflag_f32_e32 v143, v2
	v_pk_mul_f32 v[4:5], v[4:5], v[150:151]
	v_cvt_f32_ubyte0_e32 v2, v149
	v_pk_mul_f32 v[26:27], v[26:27], v[4:5]
	v_rcp_iflag_f32_e32 v4, v2
	v_cvt_f32_ubyte1_e32 v2, v149
	v_rcp_iflag_f32_e32 v5, v2
	v_cvt_f32_ubyte3_e32 v147, v144
	v_cvt_f32_ubyte2_e32 v146, v144
	v_pk_mul_f32 v[142:143], v[142:143], v[146:147]
	v_cvt_f32_ubyte2_e32 v2, v149
	v_pk_mul_f32 v[28:29], v[28:29], v[142:143]
	v_rcp_iflag_f32_e32 v142, v2
	v_cvt_f32_ubyte3_e32 v2, v149
	v_cvt_f32_ubyte1_e32 v149, v145
	v_cvt_f32_ubyte0_e32 v148, v145
	v_rcp_iflag_f32_e32 v143, v2
	v_pk_mul_f32 v[4:5], v[4:5], v[148:149]
	s_waitcnt vmcnt(0)
	v_cvt_f32_ubyte0_e32 v2, v138
	v_pk_mul_f32 v[22:23], v[22:23], v[4:5]
	v_rcp_iflag_f32_e32 v4, v2
	v_cvt_f32_ubyte1_e32 v2, v138
	v_rcp_iflag_f32_e32 v5, v2
	v_cvt_f32_ubyte3_e32 v147, v145
	v_cvt_f32_ubyte2_e32 v146, v145
	v_pk_mul_f32 v[142:143], v[142:143], v[146:147]
	v_cvt_f32_ubyte2_e32 v2, v138
	v_pk_mul_f32 v[24:25], v[24:25], v[142:143]
	v_rcp_iflag_f32_e32 v142, v2
	v_cvt_f32_ubyte3_e32 v2, v138
	v_cvt_f32_ubyte1_e32 v147, v134
	v_cvt_f32_ubyte0_e32 v146, v134
	v_rcp_iflag_f32_e32 v143, v2
	v_pk_mul_f32 v[4:5], v[4:5], v[146:147]
	v_cvt_f32_ubyte0_e32 v2, v139
	v_pk_mul_f32 v[18:19], v[18:19], v[4:5]
	v_rcp_iflag_f32_e32 v4, v2
	v_cvt_f32_ubyte1_e32 v2, v139
	v_rcp_iflag_f32_e32 v5, v2
	v_cvt_f32_ubyte2_e32 v2, v139
	v_rcp_iflag_f32_e32 v138, v2
	v_cvt_f32_ubyte3_e32 v2, v139
	v_cvt_f32_ubyte3_e32 v145, v134
	v_cvt_f32_ubyte2_e32 v144, v134
	v_rcp_iflag_f32_e32 v139, v2
	v_pk_mul_f32 v[142:143], v[142:143], v[144:145]
	v_cvt_f32_ubyte1_e32 v145, v135
	v_cvt_f32_ubyte0_e32 v144, v135
	v_pk_mul_f32 v[4:5], v[4:5], v[144:145]
	v_cvt_f32_ubyte0_e32 v2, v140
	v_pk_mul_f32 v[20:21], v[20:21], v[142:143]
	v_cvt_f32_ubyte3_e32 v143, v135
	v_cvt_f32_ubyte2_e32 v142, v135
	v_pk_mul_f32 v[14:15], v[14:15], v[4:5]
	v_rcp_iflag_f32_e32 v4, v2
	v_cvt_f32_ubyte1_e32 v2, v140
	v_pk_mul_f32 v[134:135], v[138:139], v[142:143]
	v_rcp_iflag_f32_e32 v5, v2
	v_cvt_f32_ubyte2_e32 v2, v140
	v_pk_mul_f32 v[16:17], v[16:17], v[134:135]
	v_rcp_iflag_f32_e32 v134, v2
	v_cvt_f32_ubyte3_e32 v2, v140
	v_rcp_iflag_f32_e32 v135, v2
	v_cvt_f32_ubyte1_e32 v143, v136
	v_cvt_f32_ubyte0_e32 v142, v136
	v_pk_mul_f32 v[4:5], v[4:5], v[142:143]
	v_cvt_f32_ubyte0_e32 v2, v141
	v_cvt_f32_ubyte3_e32 v139, v136
	v_cvt_f32_ubyte2_e32 v138, v136
	v_pk_mul_f32 v[10:11], v[10:11], v[4:5]
	v_rcp_iflag_f32_e32 v4, v2
	v_cvt_f32_ubyte1_e32 v2, v141
	v_pk_mul_f32 v[134:135], v[134:135], v[138:139]
	v_rcp_iflag_f32_e32 v5, v2
	v_cvt_f32_ubyte2_e32 v2, v141
	v_pk_mul_f32 v[12:13], v[12:13], v[134:135]
	v_rcp_iflag_f32_e32 v134, v2
	v_cvt_f32_ubyte3_e32 v2, v141
	v_rcp_iflag_f32_e32 v135, v2
	v_cvt_f32_ubyte3_e32 v139, v137
	v_cvt_f32_ubyte2_e32 v138, v137
	v_cvt_f32_ubyte1_e32 v141, v137
	v_cvt_f32_ubyte0_e32 v140, v137
	v_pk_mul_f32 v[4:5], v[4:5], v[140:141]
	v_pk_mul_f32 v[134:135], v[134:135], v[138:139]
	v_pk_mul_f32 v[6:7], v[6:7], v[4:5]
	v_pk_mul_f32 v[8:9], v[8:9], v[134:135]
	s_cbranch_vccnz .LBB0_3768
	s_barrier

.LBB0_3773:
	s_add_i32 s18, s53, 32
	v_mov_b32_e32 v2, v182
	v_mov_b32_e32 v179, v183
	s_ashr_i32 s19, s18, 31
	s_lshl_b64 s[18:19], s[18:19], 16
	v_lshl_add_u32 v136, v179, 4, v2
	s_add_u32 s18, s36, s18
	v_add_u32_e32 v4, s39, v136
	s_addc_u32 s19, s37, s19
	v_ashrrev_i32_e32 v5, 31, v4
	v_lshl_add_u64 v[134:135], v[4:5], 4, s[18:19]
	s_nop 0
	v_add_u32_e32 v4, 0x200, v4
	v_ashrrev_i32_e32 v5, 31, v4
	v_lshl_add_u64 v[4:5], v[4:5], 4, s[18:19]
	s_nop 0
	v_add_u32_e32 v4, s40, v136
	v_ashrrev_i32_e32 v5, 31, v4
	v_lshl_add_u64 v[4:5], v[4:5], 4, s[18:19]
	s_nop 0
	v_add_u32_e32 v4, s42, v136
	v_ashrrev_i32_e32 v5, 31, v4
	v_lshl_add_u64 v[4:5], v[4:5], 4, s[18:19]
	s_nop 0
	v_add_u32_e32 v4, s43, v136
	v_ashrrev_i32_e32 v5, 31, v4
	v_lshl_add_u64 v[4:5], v[4:5], 4, s[18:19]
	s_nop 0
	v_add_u32_e32 v4, s44, v136
	v_ashrrev_i32_e32 v5, 31, v4
	v_lshl_add_u64 v[4:5], v[4:5], 4, s[18:19]
	global_load_dwordx4 v[142:145], v[4:5], off nt
	v_add_u32_e32 v4, s45, v136
	v_ashrrev_i32_e32 v5, 31, v4
	v_lshl_add_u64 v[4:5], v[4:5], 4, s[18:19]
	global_load_dwordx4 v[138:141], v[4:5], off nt
	v_add_u32_e32 v4, s46, v136
	v_ashrrev_i32_e32 v5, 31, v4
	v_lshl_add_u64 v[4:5], v[4:5], 4, s[18:19]
	s_lshl_b32 s18, s52, 6
	s_lshl_b32 s15, s15, 2
	s_add_i32 s18, s18, s15
	s_or_b32 s15, s18, s47
	v_add_u32_e32 v178, s33, v2
	s_lshl_b32 s18, s15, 8
	global_load_dwordx4 v[134:137], v[4:5], off nt
	v_lshlrev_b32_e32 v4, 3, v179
	v_ashrrev_i32_e32 v179, 31, v178
	s_ashr_i32 s19, s18, 31
	v_ashrrev_i32_e32 v5, 31, v4
	v_lshl_add_u64 v[4:5], v[4:5], 1, s[12:13]
	s_or_b32 s20, s18, 0x200
	s_ashr_i32 s21, s20, 31
	s_and_b64 vcc, exec, s[4:5]
	s_movk_i32 s55, 0x1ff
	s_mov_b64 s[56:57], 0x10000
	s_nop 0
	v_cvt_f32_ubyte1_e32 v181, v240
	v_cvt_f32_ubyte0_e32 v180, v240
	v_pk_mul_f32 v[180:181], v[180:181], s[78:79] op_sel_hi:[1,0]
	s_nop 0
	v_pk_mul_f32 v[130:131], v[130:131], v[180:181]
	v_cvt_f32_ubyte1_e32 v181, v241
	v_cvt_f32_ubyte0_e32 v180, v241
	v_pk_mul_f32 v[180:181], v[180:181], s[78:79] op_sel_hi:[1,0]
	s_nop 0
	v_pk_mul_f32 v[180:181], v[126:127], v[180:181]
	v_cvt_f32_ubyte3_e32 v127, v240
	v_cvt_f32_ubyte2_e32 v126, v240
	v_pk_mul_f32 v[126:127], v[126:127], s[78:79] op_sel_hi:[1,0]
	s_nop 0
	v_pk_mul_f32 v[132:133], v[132:133], v[126:127]
	v_cvt_f32_ubyte3_e32 v127, v241
	v_cvt_f32_ubyte2_e32 v126, v241
	v_pk_mul_f32 v[126:127], v[126:127], s[78:79] op_sel_hi:[1,0]
	s_nop 0
	v_pk_mul_f32 v[162:163], v[128:129], v[126:127]
	v_cvt_pk_bf16_f32 v126, v130, v131
	v_lshl_add_u64 v[130:131], v[178:179], 0, s[18:19]
	v_lshlrev_b64 v[130:131], 7, v[130:131]
	v_cvt_pk_bf16_f32 v127, v132, v133
	v_cvt_pk_bf16_f32 v128, v180, v181
	v_cvt_pk_bf16_f32 v129, v162, v163
	v_lshl_add_u64 v[130:131], v[4:5], 0, v[130:131]
	global_store_dwordx4 v[130:131], v[126:129], off
	s_nop 1
	v_cvt_f32_ubyte1_e32 v127, v242
	v_cvt_f32_ubyte0_e32 v126, v242
	v_pk_mul_f32 v[126:127], v[126:127], s[78:79] op_sel_hi:[1,0]
	s_nop 0
	v_pk_mul_f32 v[122:123], v[122:123], v[126:127]
	v_cvt_f32_ubyte1_e32 v127, v243
	v_cvt_f32_ubyte0_e32 v126, v243
	v_pk_mul_f32 v[126:127], v[126:127], s[78:79] op_sel_hi:[1,0]
	s_nop 0
	v_pk_mul_f32 v[126:127], v[118:119], v[126:127]
	v_cvt_f32_ubyte3_e32 v119, v242
	v_cvt_f32_ubyte2_e32 v118, v242
	v_pk_mul_f32 v[118:119], v[118:119], s[78:79] op_sel_hi:[1,0]
	s_nop 0
	v_pk_mul_f32 v[124:125], v[124:125], v[118:119]
	v_cvt_f32_ubyte3_e32 v119, v243
	v_cvt_f32_ubyte2_e32 v118, v243
	v_pk_mul_f32 v[118:119], v[118:119], s[78:79] op_sel_hi:[1,0]
	s_nop 0
	v_pk_mul_f32 v[128:129], v[120:121], v[118:119]
	v_cvt_pk_bf16_f32 v118, v122, v123
	v_lshl_add_u64 v[122:123], v[178:179], 0, s[20:21]
	v_lshlrev_b64 v[122:123], 7, v[122:123]
	v_cvt_pk_bf16_f32 v119, v124, v125
	v_cvt_pk_bf16_f32 v120, v126, v127
	v_cvt_pk_bf16_f32 v121, v128, v129
	v_lshl_add_u64 v[122:123], v[4:5], 0, v[122:123]
	global_store_dwordx4 v[122:123], v[118:121], off
	s_nop 1
	v_cvt_f32_ubyte1_e32 v121, v244
	v_cvt_f32_ubyte0_e32 v120, v244
	v_pk_mul_f32 v[120:121], v[120:121], s[78:79] op_sel_hi:[1,0]
	v_add_u32_e32 v118, 16, v178
	v_pk_mul_f32 v[114:115], v[114:115], v[120:121]
	v_cvt_f32_ubyte1_e32 v121, v245
	v_cvt_f32_ubyte0_e32 v120, v245
	v_pk_mul_f32 v[120:121], v[120:121], s[78:79] op_sel_hi:[1,0]
	v_ashrrev_i32_e32 v119, 31, v118
	v_pk_mul_f32 v[120:121], v[110:111], v[120:121]
	v_cvt_f32_ubyte3_e32 v111, v244
	v_cvt_f32_ubyte2_e32 v110, v244
	v_pk_mul_f32 v[110:111], v[110:111], s[78:79] op_sel_hi:[1,0]
	s_nop 0
	v_pk_mul_f32 v[116:117], v[116:117], v[110:111]
	v_cvt_f32_ubyte3_e32 v111, v245
	v_cvt_f32_ubyte2_e32 v110, v245
	v_pk_mul_f32 v[110:111], v[110:111], s[78:79] op_sel_hi:[1,0]
	s_nop 0
	v_pk_mul_f32 v[122:123], v[112:113], v[110:111]
	v_cvt_pk_bf16_f32 v110, v114, v115
	v_lshl_add_u64 v[114:115], v[118:119], 0, s[18:19]
	v_lshlrev_b64 v[114:115], 7, v[114:115]
	v_cvt_pk_bf16_f32 v111, v116, v117
	v_cvt_pk_bf16_f32 v112, v120, v121
	v_cvt_pk_bf16_f32 v113, v122, v123
	v_lshl_add_u64 v[114:115], v[4:5], 0, v[114:115]
	global_store_dwordx4 v[114:115], v[110:113], off
	s_nop 1
	v_cvt_f32_ubyte1_e32 v111, v246
	v_cvt_f32_ubyte0_e32 v110, v246
	v_pk_mul_f32 v[110:111], v[110:111], s[78:79] op_sel_hi:[1,0]
	s_nop 0
	v_pk_mul_f32 v[106:107], v[106:107], v[110:111]
	v_cvt_f32_ubyte1_e32 v111, v247
	v_cvt_f32_ubyte0_e32 v110, v247
	v_pk_mul_f32 v[110:111], v[110:111], s[78:79] op_sel_hi:[1,0]
	s_nop 0
	v_pk_mul_f32 v[110:111], v[102:103], v[110:111]
	v_cvt_f32_ubyte3_e32 v103, v246
	v_cvt_f32_ubyte2_e32 v102, v246
	v_pk_mul_f32 v[102:103], v[102:103], s[78:79] op_sel_hi:[1,0]
	s_nop 0
	v_pk_mul_f32 v[108:109], v[108:109], v[102:103]
	v_cvt_f32_ubyte3_e32 v103, v247
	v_cvt_f32_ubyte2_e32 v102, v247
	v_pk_mul_f32 v[102:103], v[102:103], s[78:79] op_sel_hi:[1,0]
	s_nop 0
	v_pk_mul_f32 v[112:113], v[104:105], v[102:103]
	v_cvt_pk_bf16_f32 v102, v106, v107
	v_lshl_add_u64 v[106:107], v[118:119], 0, s[20:21]
	v_lshlrev_b64 v[106:107], 7, v[106:107]
	v_cvt_pk_bf16_f32 v103, v108, v109
	v_cvt_pk_bf16_f32 v104, v110, v111
	v_cvt_pk_bf16_f32 v105, v112, v113
	v_lshl_add_u64 v[106:107], v[4:5], 0, v[106:107]
	global_store_dwordx4 v[106:107], v[102:105], off
	s_nop 1
	v_cvt_f32_ubyte1_e32 v105, v248
	v_cvt_f32_ubyte0_e32 v104, v248
	v_pk_mul_f32 v[104:105], v[104:105], s[78:79] op_sel_hi:[1,0]
	v_add_u32_e32 v102, 32, v178
	v_pk_mul_f32 v[98:99], v[98:99], v[104:105]
	v_cvt_f32_ubyte1_e32 v105, v249
	v_cvt_f32_ubyte0_e32 v104, v249
	v_pk_mul_f32 v[104:105], v[104:105], s[78:79] op_sel_hi:[1,0]
	v_ashrrev_i32_e32 v103, 31, v102
	v_pk_mul_f32 v[104:105], v[94:95], v[104:105]
	v_cvt_f32_ubyte3_e32 v95, v248
	v_cvt_f32_ubyte2_e32 v94, v248
	v_pk_mul_f32 v[94:95], v[94:95], s[78:79] op_sel_hi:[1,0]
	s_nop 0
	v_pk_mul_f32 v[100:101], v[100:101], v[94:95]
	v_cvt_f32_ubyte3_e32 v95, v249
	v_cvt_f32_ubyte2_e32 v94, v249
	v_pk_mul_f32 v[94:95], v[94:95], s[78:79] op_sel_hi:[1,0]
	s_nop 0
	v_pk_mul_f32 v[106:107], v[96:97], v[94:95]
	v_cvt_pk_bf16_f32 v94, v98, v99
	v_lshl_add_u64 v[98:99], v[102:103], 0, s[18:19]
	v_lshlrev_b64 v[98:99], 7, v[98:99]
	v_cvt_pk_bf16_f32 v95, v100, v101
	v_cvt_pk_bf16_f32 v96, v104, v105
	v_cvt_pk_bf16_f32 v97, v106, v107
	v_lshl_add_u64 v[98:99], v[4:5], 0, v[98:99]
	global_store_dwordx4 v[98:99], v[94:97], off
	s_nop 1
	v_cvt_f32_ubyte1_e32 v95, v250
	v_cvt_f32_ubyte0_e32 v94, v250
	v_pk_mul_f32 v[94:95], v[94:95], s[78:79] op_sel_hi:[1,0]
	s_nop 0
	v_pk_mul_f32 v[90:91], v[90:91], v[94:95]
	v_cvt_f32_ubyte1_e32 v95, v251
	v_cvt_f32_ubyte0_e32 v94, v251
	v_pk_mul_f32 v[94:95], v[94:95], s[78:79] op_sel_hi:[1,0]
	s_nop 0
	v_pk_mul_f32 v[94:95], v[86:87], v[94:95]
	v_cvt_f32_ubyte3_e32 v87, v250
	v_cvt_f32_ubyte2_e32 v86, v250
	v_pk_mul_f32 v[86:87], v[86:87], s[78:79] op_sel_hi:[1,0]
	s_nop 0
	v_pk_mul_f32 v[92:93], v[92:93], v[86:87]
	v_cvt_f32_ubyte3_e32 v87, v251
	v_cvt_f32_ubyte2_e32 v86, v251
	v_pk_mul_f32 v[86:87], v[86:87], s[78:79] op_sel_hi:[1,0]
	s_nop 0
	v_pk_mul_f32 v[96:97], v[88:89], v[86:87]
	v_cvt_pk_bf16_f32 v86, v90, v91
	v_lshl_add_u64 v[90:91], v[102:103], 0, s[20:21]
	v_lshlrev_b64 v[90:91], 7, v[90:91]
	v_cvt_pk_bf16_f32 v87, v92, v93
	v_cvt_pk_bf16_f32 v88, v94, v95
	v_cvt_pk_bf16_f32 v89, v96, v97
	v_lshl_add_u64 v[90:91], v[4:5], 0, v[90:91]
	global_store_dwordx4 v[90:91], v[86:89], off
	s_nop 1
	v_cvt_f32_ubyte1_e32 v89, v218
	v_cvt_f32_ubyte0_e32 v88, v218
	v_pk_mul_f32 v[88:89], v[88:89], s[78:79] op_sel_hi:[1,0]
	v_add_u32_e32 v86, 48, v178
	v_pk_mul_f32 v[82:83], v[82:83], v[88:89]
	v_cvt_f32_ubyte1_e32 v89, v219
	v_cvt_f32_ubyte0_e32 v88, v219
	v_pk_mul_f32 v[88:89], v[88:89], s[78:79] op_sel_hi:[1,0]
	v_ashrrev_i32_e32 v87, 31, v86
	v_pk_mul_f32 v[88:89], v[78:79], v[88:89]
	v_cvt_f32_ubyte3_e32 v79, v218
	v_cvt_f32_ubyte2_e32 v78, v218
	v_pk_mul_f32 v[78:79], v[78:79], s[78:79] op_sel_hi:[1,0]
	s_nop 0
	v_pk_mul_f32 v[84:85], v[84:85], v[78:79]
	v_cvt_f32_ubyte3_e32 v79, v219
	v_cvt_f32_ubyte2_e32 v78, v219
	v_pk_mul_f32 v[78:79], v[78:79], s[78:79] op_sel_hi:[1,0]
	s_nop 0
	v_pk_mul_f32 v[90:91], v[80:81], v[78:79]
	v_cvt_pk_bf16_f32 v78, v82, v83
	v_lshl_add_u64 v[82:83], v[86:87], 0, s[18:19]
	v_lshlrev_b64 v[82:83], 7, v[82:83]
	v_cvt_pk_bf16_f32 v79, v84, v85
	v_cvt_pk_bf16_f32 v80, v88, v89
	v_cvt_pk_bf16_f32 v81, v90, v91
	v_lshl_add_u64 v[82:83], v[4:5], 0, v[82:83]
	global_store_dwordx4 v[82:83], v[78:81], off
	s_nop 1
	v_cvt_f32_ubyte1_e32 v79, v220
	v_cvt_f32_ubyte0_e32 v78, v220
	v_pk_mul_f32 v[78:79], v[78:79], s[78:79] op_sel_hi:[1,0]
	s_nop 0
	v_pk_mul_f32 v[74:75], v[74:75], v[78:79]
	v_cvt_f32_ubyte1_e32 v79, v221
	v_cvt_f32_ubyte0_e32 v78, v221
	v_pk_mul_f32 v[78:79], v[78:79], s[78:79] op_sel_hi:[1,0]
	s_nop 0
	v_pk_mul_f32 v[78:79], v[70:71], v[78:79]
	v_cvt_f32_ubyte3_e32 v71, v220
	v_cvt_f32_ubyte2_e32 v70, v220
	v_pk_mul_f32 v[70:71], v[70:71], s[78:79] op_sel_hi:[1,0]
	s_nop 0
	v_pk_mul_f32 v[76:77], v[76:77], v[70:71]
	v_cvt_f32_ubyte3_e32 v71, v221
	v_cvt_f32_ubyte2_e32 v70, v221
	v_pk_mul_f32 v[70:71], v[70:71], s[78:79] op_sel_hi:[1,0]
	s_nop 0
	v_pk_mul_f32 v[80:81], v[72:73], v[70:71]
	v_cvt_pk_bf16_f32 v70, v74, v75
	v_lshl_add_u64 v[74:75], v[86:87], 0, s[20:21]
	v_lshlrev_b64 v[74:75], 7, v[74:75]
	v_cvt_pk_bf16_f32 v71, v76, v77
	v_cvt_pk_bf16_f32 v72, v78, v79
	v_cvt_pk_bf16_f32 v73, v80, v81
	v_lshl_add_u64 v[74:75], v[4:5], 0, v[74:75]
	global_store_dwordx4 v[74:75], v[70:73], off
	s_nop 1
	v_cvt_f32_ubyte1_e32 v73, v222
	v_cvt_f32_ubyte0_e32 v72, v222
	v_pk_mul_f32 v[72:73], v[72:73], s[78:79] op_sel_hi:[1,0]
	v_add_u32_e32 v70, 0x80, v178
	v_pk_mul_f32 v[66:67], v[66:67], v[72:73]
	v_cvt_f32_ubyte1_e32 v73, v223
	v_cvt_f32_ubyte0_e32 v72, v223
	v_pk_mul_f32 v[72:73], v[72:73], s[78:79] op_sel_hi:[1,0]
	v_ashrrev_i32_e32 v71, 31, v70
	v_pk_mul_f32 v[72:73], v[62:63], v[72:73]
	v_cvt_f32_ubyte3_e32 v63, v222
	v_cvt_f32_ubyte2_e32 v62, v222
	v_pk_mul_f32 v[62:63], v[62:63], s[78:79] op_sel_hi:[1,0]
	s_nop 0
	v_pk_mul_f32 v[68:69], v[68:69], v[62:63]
	v_cvt_f32_ubyte3_e32 v63, v223
	v_cvt_f32_ubyte2_e32 v62, v223
	v_pk_mul_f32 v[62:63], v[62:63], s[78:79] op_sel_hi:[1,0]
	s_nop 0
	v_pk_mul_f32 v[74:75], v[64:65], v[62:63]
	v_cvt_pk_bf16_f32 v62, v66, v67
	v_lshl_add_u64 v[66:67], v[70:71], 0, s[18:19]
	v_lshlrev_b64 v[66:67], 7, v[66:67]
	v_cvt_pk_bf16_f32 v63, v68, v69
	v_cvt_pk_bf16_f32 v64, v72, v73
	v_cvt_pk_bf16_f32 v65, v74, v75
	v_lshl_add_u64 v[66:67], v[4:5], 0, v[66:67]
	global_store_dwordx4 v[66:67], v[62:65], off
	s_nop 1
	v_cvt_f32_ubyte1_e32 v63, v224
	v_cvt_f32_ubyte0_e32 v62, v224
	v_pk_mul_f32 v[62:63], v[62:63], s[78:79] op_sel_hi:[1,0]
	s_nop 0
	v_pk_mul_f32 v[58:59], v[58:59], v[62:63]
	v_cvt_f32_ubyte1_e32 v63, v225
	v_cvt_f32_ubyte0_e32 v62, v225
	v_pk_mul_f32 v[62:63], v[62:63], s[78:79] op_sel_hi:[1,0]
	s_nop 0
	v_pk_mul_f32 v[62:63], v[54:55], v[62:63]
	v_cvt_f32_ubyte3_e32 v55, v224
	v_cvt_f32_ubyte2_e32 v54, v224
	v_pk_mul_f32 v[54:55], v[54:55], s[78:79] op_sel_hi:[1,0]
	s_nop 0
	v_pk_mul_f32 v[60:61], v[60:61], v[54:55]
	v_cvt_f32_ubyte3_e32 v55, v225
	v_cvt_f32_ubyte2_e32 v54, v225
	v_pk_mul_f32 v[54:55], v[54:55], s[78:79] op_sel_hi:[1,0]
	s_nop 0
	v_pk_mul_f32 v[64:65], v[56:57], v[54:55]
	v_cvt_pk_bf16_f32 v54, v58, v59
	v_lshl_add_u64 v[58:59], v[70:71], 0, s[20:21]
	v_lshlrev_b64 v[58:59], 7, v[58:59]
	v_cvt_pk_bf16_f32 v55, v60, v61
	v_cvt_pk_bf16_f32 v56, v62, v63
	v_cvt_pk_bf16_f32 v57, v64, v65
	v_lshl_add_u64 v[58:59], v[4:5], 0, v[58:59]
	global_store_dwordx4 v[58:59], v[54:57], off
	s_nop 1
	s_waitcnt vmcnt(12)
	v_cvt_f32_ubyte1_e32 v57, v142
	v_cvt_f32_ubyte0_e32 v56, v142
	v_pk_mul_f32 v[56:57], v[56:57], s[78:79] op_sel_hi:[1,0]
	v_add_u32_e32 v54, 0x90, v178
	v_pk_mul_f32 v[50:51], v[50:51], v[56:57]
	v_cvt_f32_ubyte1_e32 v57, v143
	v_cvt_f32_ubyte0_e32 v56, v143
	v_pk_mul_f32 v[56:57], v[56:57], s[78:79] op_sel_hi:[1,0]
	v_ashrrev_i32_e32 v55, 31, v54
	v_pk_mul_f32 v[56:57], v[46:47], v[56:57]
	v_cvt_f32_ubyte3_e32 v47, v142
	v_cvt_f32_ubyte2_e32 v46, v142
	v_pk_mul_f32 v[46:47], v[46:47], s[78:79] op_sel_hi:[1,0]
	s_nop 0
	v_pk_mul_f32 v[52:53], v[52:53], v[46:47]
	v_cvt_f32_ubyte3_e32 v47, v143
	v_cvt_f32_ubyte2_e32 v46, v143
	v_pk_mul_f32 v[46:47], v[46:47], s[78:79] op_sel_hi:[1,0]
	s_nop 0
	v_pk_mul_f32 v[58:59], v[48:49], v[46:47]
	v_cvt_pk_bf16_f32 v46, v50, v51
	v_lshl_add_u64 v[50:51], v[54:55], 0, s[18:19]
	v_lshlrev_b64 v[50:51], 7, v[50:51]
	v_cvt_pk_bf16_f32 v47, v52, v53
	v_cvt_pk_bf16_f32 v48, v56, v57
	v_cvt_pk_bf16_f32 v49, v58, v59
	v_lshl_add_u64 v[50:51], v[4:5], 0, v[50:51]
	global_store_dwordx4 v[50:51], v[46:49], off
	s_nop 1
	v_cvt_f32_ubyte1_e32 v47, v144
	v_cvt_f32_ubyte0_e32 v46, v144
	v_pk_mul_f32 v[46:47], v[46:47], s[78:79] op_sel_hi:[1,0]
	s_nop 0
	v_pk_mul_f32 v[42:43], v[42:43], v[46:47]
	v_cvt_f32_ubyte1_e32 v47, v145
	v_cvt_f32_ubyte0_e32 v46, v145
	v_pk_mul_f32 v[46:47], v[46:47], s[78:79] op_sel_hi:[1,0]
	s_nop 0
	v_pk_mul_f32 v[46:47], v[38:39], v[46:47]
	v_cvt_f32_ubyte3_e32 v39, v144
	v_cvt_f32_ubyte2_e32 v38, v144
	v_pk_mul_f32 v[38:39], v[38:39], s[78:79] op_sel_hi:[1,0]
	s_nop 0
	v_pk_mul_f32 v[44:45], v[44:45], v[38:39]
	v_cvt_f32_ubyte3_e32 v39, v145
	v_cvt_f32_ubyte2_e32 v38, v145
	v_pk_mul_f32 v[38:39], v[38:39], s[78:79] op_sel_hi:[1,0]
	s_nop 0
	v_pk_mul_f32 v[48:49], v[40:41], v[38:39]
	v_cvt_pk_bf16_f32 v38, v42, v43
	v_lshl_add_u64 v[42:43], v[54:55], 0, s[20:21]
	v_lshlrev_b64 v[42:43], 7, v[42:43]
	v_cvt_pk_bf16_f32 v39, v44, v45
	v_cvt_pk_bf16_f32 v40, v46, v47
	v_cvt_pk_bf16_f32 v41, v48, v49
	v_lshl_add_u64 v[42:43], v[4:5], 0, v[42:43]
	global_store_dwordx4 v[42:43], v[38:41], off
	s_nop 1
	s_waitcnt vmcnt(13)
	v_cvt_f32_ubyte1_e32 v41, v138
	v_cvt_f32_ubyte0_e32 v40, v138
	v_pk_mul_f32 v[40:41], v[40:41], s[78:79] op_sel_hi:[1,0]
	v_add_u32_e32 v38, 0xa0, v178
	v_pk_mul_f32 v[34:35], v[34:35], v[40:41]
	v_cvt_f32_ubyte1_e32 v41, v139
	v_cvt_f32_ubyte0_e32 v40, v139
	v_pk_mul_f32 v[40:41], v[40:41], s[78:79] op_sel_hi:[1,0]
	v_ashrrev_i32_e32 v39, 31, v38
	v_pk_mul_f32 v[40:41], v[30:31], v[40:41]
	v_cvt_f32_ubyte3_e32 v31, v138
	v_cvt_f32_ubyte2_e32 v30, v138
	v_pk_mul_f32 v[30:31], v[30:31], s[78:79] op_sel_hi:[1,0]
	s_nop 0
	v_pk_mul_f32 v[36:37], v[36:37], v[30:31]
	v_cvt_f32_ubyte3_e32 v31, v139
	v_cvt_f32_ubyte2_e32 v30, v139
	v_pk_mul_f32 v[30:31], v[30:31], s[78:79] op_sel_hi:[1,0]
	s_nop 0
	v_pk_mul_f32 v[42:43], v[32:33], v[30:31]
	v_cvt_pk_bf16_f32 v30, v34, v35
	v_lshl_add_u64 v[34:35], v[38:39], 0, s[18:19]
	v_lshlrev_b64 v[34:35], 7, v[34:35]
	v_cvt_pk_bf16_f32 v31, v36, v37
	v_cvt_pk_bf16_f32 v32, v40, v41
	v_cvt_pk_bf16_f32 v33, v42, v43
	v_lshl_add_u64 v[34:35], v[4:5], 0, v[34:35]
	global_store_dwordx4 v[34:35], v[30:33], off
	s_nop 1
	v_cvt_f32_ubyte1_e32 v31, v140
	v_cvt_f32_ubyte0_e32 v30, v140
	v_pk_mul_f32 v[30:31], v[30:31], s[78:79] op_sel_hi:[1,0]
	s_nop 0
	v_pk_mul_f32 v[26:27], v[26:27], v[30:31]
	v_cvt_f32_ubyte1_e32 v31, v141
	v_cvt_f32_ubyte0_e32 v30, v141
	v_pk_mul_f32 v[30:31], v[30:31], s[78:79] op_sel_hi:[1,0]
	s_nop 0
	v_pk_mul_f32 v[30:31], v[22:23], v[30:31]
	v_cvt_f32_ubyte3_e32 v23, v140
	v_cvt_f32_ubyte2_e32 v22, v140
	v_pk_mul_f32 v[22:23], v[22:23], s[78:79] op_sel_hi:[1,0]
	s_nop 0
	v_pk_mul_f32 v[28:29], v[28:29], v[22:23]
	v_cvt_f32_ubyte3_e32 v23, v141
	v_cvt_f32_ubyte2_e32 v22, v141
	v_pk_mul_f32 v[22:23], v[22:23], s[78:79] op_sel_hi:[1,0]
	s_nop 0
	v_pk_mul_f32 v[32:33], v[24:25], v[22:23]
	v_cvt_pk_bf16_f32 v22, v26, v27
	v_lshl_add_u64 v[26:27], v[38:39], 0, s[20:21]
	v_lshlrev_b64 v[26:27], 7, v[26:27]
	v_cvt_pk_bf16_f32 v23, v28, v29
	v_cvt_pk_bf16_f32 v24, v30, v31
	v_cvt_pk_bf16_f32 v25, v32, v33
	v_lshl_add_u64 v[26:27], v[4:5], 0, v[26:27]
	global_store_dwordx4 v[26:27], v[22:25], off
	s_nop 1
	s_waitcnt vmcnt(14)
	v_cvt_f32_ubyte1_e32 v25, v134
	v_cvt_f32_ubyte0_e32 v24, v134
	v_pk_mul_f32 v[24:25], v[24:25], s[78:79] op_sel_hi:[1,0]
	v_add_u32_e32 v22, 0xb0, v178
	v_pk_mul_f32 v[18:19], v[18:19], v[24:25]
	v_cvt_f32_ubyte1_e32 v25, v135
	v_cvt_f32_ubyte0_e32 v24, v135
	v_pk_mul_f32 v[24:25], v[24:25], s[78:79] op_sel_hi:[1,0]
	v_ashrrev_i32_e32 v23, 31, v22
	v_pk_mul_f32 v[24:25], v[14:15], v[24:25]
	v_cvt_f32_ubyte3_e32 v15, v134
	v_cvt_f32_ubyte2_e32 v14, v134
	v_pk_mul_f32 v[14:15], v[14:15], s[78:79] op_sel_hi:[1,0]
	s_nop 0
	v_pk_mul_f32 v[20:21], v[20:21], v[14:15]
	v_cvt_f32_ubyte3_e32 v15, v135
	v_cvt_f32_ubyte2_e32 v14, v135
	v_pk_mul_f32 v[14:15], v[14:15], s[78:79] op_sel_hi:[1,0]
	s_nop 0
	v_pk_mul_f32 v[26:27], v[16:17], v[14:15]
	v_cvt_pk_bf16_f32 v14, v18, v19
	v_lshl_add_u64 v[18:19], v[22:23], 0, s[18:19]
	v_lshlrev_b64 v[18:19], 7, v[18:19]
	v_cvt_pk_bf16_f32 v15, v20, v21
	v_cvt_pk_bf16_f32 v16, v24, v25
	v_cvt_pk_bf16_f32 v17, v26, v27
	v_lshl_add_u64 v[18:19], v[4:5], 0, v[18:19]
	global_store_dwordx4 v[18:19], v[14:17], off
	s_mov_b64 s[18:19], -1
	s_nop 0
	v_cvt_f32_ubyte1_e32 v15, v136
	v_cvt_f32_ubyte0_e32 v14, v136
	v_pk_mul_f32 v[14:15], v[14:15], s[78:79] op_sel_hi:[1,0]
	s_nop 0
	v_pk_mul_f32 v[10:11], v[10:11], v[14:15]
	v_cvt_f32_ubyte1_e32 v15, v137
	v_cvt_f32_ubyte0_e32 v14, v137
	v_pk_mul_f32 v[14:15], v[14:15], s[78:79] op_sel_hi:[1,0]
	s_nop 0
	v_pk_mul_f32 v[14:15], v[6:7], v[14:15]
	v_cvt_f32_ubyte3_e32 v7, v136
	v_cvt_f32_ubyte2_e32 v6, v136
	v_pk_mul_f32 v[6:7], v[6:7], s[78:79] op_sel_hi:[1,0]
	s_nop 0
	v_pk_mul_f32 v[12:13], v[12:13], v[6:7]
	v_cvt_f32_ubyte3_e32 v7, v137
	v_cvt_f32_ubyte2_e32 v6, v137
	v_pk_mul_f32 v[6:7], v[6:7], s[78:79] op_sel_hi:[1,0]
	s_nop 0
	v_pk_mul_f32 v[16:17], v[8:9], v[6:7]
	v_cvt_pk_bf16_f32 v6, v10, v11
	v_lshl_add_u64 v[10:11], v[22:23], 0, s[20:21]
	v_lshlrev_b64 v[10:11], 7, v[10:11]
	v_cvt_pk_bf16_f32 v7, v12, v13
	v_cvt_pk_bf16_f32 v8, v14, v15
	v_cvt_pk_bf16_f32 v9, v16, v17
	v_lshl_add_u64 v[4:5], v[4:5], 0, v[10:11]
	global_store_dwordx4 v[4:5], v[6:9], off
	s_cbranch_vccnz .LBB0_3749
	s_andn2_b64 vcc, exec, s[8:9]
	s_cbranch_vccnz .LBB0_3748
	s_barrier
	s_branch .LBB0_3748

.LBB0_3831:
	s_or_b64 exec, exec, s[4:5]
	v_mov_b32_e32 v218, 0x260
	v_mbcnt_lo_u32_b32 v219, -1, 0
	v_mbcnt_hi_u32_b32 v219, -1, v219
	v_mov_b32_e32 v220, 0x41b17218
	v_mov_b32_e32 v221, 0x60
	v_mov_b32_e32 v222, 0x1ffff3
	v_mov_b32_e32 v223, 0x6000
	v_mov_b32_e32 v224, 0xff800000
	v_mov_b32_e32 v225, 0xc0
	v_readlane_b32 s0, v254, 19
	s_mov_b64 s[4:5], s[64:65]
	v_mov_b32_e32 v14, v0
	v_readlane_b32 s1, v254, 20
	s_waitcnt lgkmcnt(0)
	s_barrier
	s_and_b64 vcc, exec, s[0:1]
	v_readfirstlane_b32 s8, v14
	s_cbranch_vccz .LBB0_3851
	v_lshlrev_b32_e32 v2, 4, v14
	v_add_u32_e32 v4, 0x2000, v2
	v_ashrrev_i32_e32 v5, 31, v4
	v_lshrrev_b32_e32 v5, 22, v5
	v_add_u32_e32 v5, v4, v5
	v_ashrrev_i32_e32 v8, 10, v5
	s_load_dwordx2 s[4:5], s[4:5], 0x98
	v_mul_i32_i24_e32 v5, 0x400, v8
	v_sub_u32_e32 v4, v4, v5
	v_lshrrev_b32_e32 v5, 4, v4
	v_bitop3_b32 v4, v5, v4, 32 bitop3:0x6c
	v_readlane_b32 s0, v255, 21
	v_ashrrev_i32_e32 v5, 31, v4
	s_waitcnt lgkmcnt(0)
	s_add_u32 s6, s4, s0
	v_lshrrev_b32_e32 v5, 26, v5
	s_addc_u32 s7, s5, 0
	v_add_u32_e32 v5, v4, v5
	v_lshlrev_b32_e32 v6, 3, v8
	s_add_u32 s0, s4, 0x46800000
	v_ashrrev_i32_e32 v9, 6, v5
	v_and_b32_e32 v6, -16, v6
	s_addc_u32 s1, s5, 0
	v_add_u32_e32 v6, v9, v6
	s_add_u32 s14, s6, 0x12500000
	v_and_b32_e32 v7, 3, v9
	s_mov_b32 s6, 0x7ffe0
	v_lshrrev_b32_e32 v10, 2, v6
	v_lshlrev_b32_e32 v11, 1, v6
	v_and_b32_e32 v5, 0xc0, v5
	v_and_or_b32 v7, v6, s6, v7
	v_and_b32_e32 v10, 4, v10
	v_and_b32_e32 v11, 24, v11
	v_sub_u32_e32 v4, v4, v5
	v_or3_b32 v7, v7, v10, v11
	v_lshlrev_b32_e32 v10, 5, v8
	v_ashrrev_i16_sdwa v4, v216, sext(v4) dst_sel:DWORD dst_unused:UNUSED_PAD src0_sel:DWORD src1_sel:BYTE_0
	v_and_b32_e32 v11, 32, v10
	v_bfe_i32 v10, v4, 0, 16
	v_add_lshl_u32 v4, v11, v10, 1
	v_lshl_add_u32 v132, v7, 13, v4
	v_lshl_add_u32 v134, v6, 7, v4
	v_bfe_i32 v4, v14, 27, 1
	v_lshrrev_b32_e32 v4, 22, v4
	v_add_u32_e32 v4, v2, v4
	v_and_b32_e32 v4, 0xfffffc00, v4
	v_sub_u32_e32 v2, v2, v4
	v_lshrrev_b32_e32 v4, 4, v2
	v_ashrrev_i32_e32 v5, 31, v14
	v_bitop3_b32 v2, v4, v2, 32 bitop3:0x6c
	v_lshrrev_b32_e32 v5, 26, v5
	v_ashrrev_i32_e32 v4, 31, v2
	v_add_u32_e32 v5, v14, v5
	v_lshrrev_b32_e32 v4, 26, v4
	v_ashrrev_i32_e32 v12, 6, v5
	v_add_u32_e32 v4, v2, v4
	v_lshlrev_b32_e32 v5, 3, v12
	v_ashrrev_i32_e32 v11, 6, v4
	v_and_b32_e32 v5, -16, v5
	v_add_u32_e32 v5, v11, v5
	v_and_b32_e32 v6, 3, v11
	v_lshrrev_b32_e32 v7, 2, v5
	v_lshlrev_b32_e32 v13, 1, v5
	v_and_b32_e32 v4, 0xc0, v4
	s_addc_u32 s15, s7, 0
	s_ashr_i32 s9, s8, 6
	v_and_or_b32 v6, v5, s6, v6
	v_and_b32_e32 v7, 4, v7
	v_and_b32_e32 v13, 24, v13
	v_sub_u32_e32 v2, v2, v4
	s_ashr_i32 s10, s8, 8
	s_lshl_b32 s28, s9, 10
	v_or3_b32 v6, v6, v7, v13
	v_lshlrev_b32_e32 v7, 5, v12
	v_ashrrev_i16_sdwa v2, v216, sext(v2) dst_sel:DWORD dst_unused:UNUSED_PAD src0_sel:DWORD src1_sel:BYTE_0
	v_readlane_b32 s6, v254, 34
	v_and_b32_e32 v7, 32, v7
	v_bfe_i32 v13, v2, 0, 16
	v_readlane_b32 s7, v254, 35
	s_add_u32 s20, s14, s6
	v_add_lshl_u32 v4, v7, v13, 1
	s_addc_u32 s21, s15, s7
	s_add_i32 s29, s28, 0
	v_lshl_add_u32 v2, v6, 13, v4
	s_add_i32 m0, s29, 0x10000
	v_lshl_add_u32 v136, v5, 7, v4
	global_load_lds_dwordx4 v2, s[20:21]
	s_add_i32 m0, s29, 0x12000
	s_add_u32 s6, s20, 0x100000
	global_load_lds_dwordx4 v132, s[20:21]
	s_addc_u32 s7, s21, 0
	s_add_i32 m0, s29, 0x14000
	v_mov_b32_e32 v133, v3
	global_load_lds_dwordx4 v2, s[6:7]
	s_add_i32 m0, s29, 0x16000
	v_lshl_add_u64 v[4:5], s[20:21], 0, v[2:3]
	global_load_lds_dwordx4 v132, s[6:7]
	v_readlane_b32 s6, v254, 56
	v_readlane_b32 s7, v254, 57
	s_add_u32 s22, s0, s6
	s_addc_u32 s23, s1, s7
	s_add_i32 s30, s29, 0x2000
	s_mov_b32 m0, s29
	s_add_u32 s6, s22, 0x4000
	global_load_lds_dwordx4 v136, s[22:23]
	s_mov_b32 m0, s30
	s_addc_u32 s7, s23, 0
	s_add_i32 s31, s29, 0x4000
	global_load_lds_dwordx4 v134, s[22:23]
	s_mov_b32 m0, s31
	s_add_i32 s33, s29, 0x6000
	global_load_lds_dwordx4 v136, s[6:7]
	s_mov_b32 m0, s33
	s_cmp_eq_u32 s10, 1
	global_load_lds_dwordx4 v134, s[6:7]
	s_cselect_b64 s[6:7], -1, 0
	s_cmp_lg_u32 s10, 1
	v_lshl_add_u64 v[6:7], s[20:21], 0, v[132:133]
	s_cbranch_scc1 .LBB0_3834
	s_barrier
